# GLA scan steady-state step: both A-operand LDS read streams issued 4 reads ahead into fresh registers
# speedup vs baseline: 1.0291x; 1.0029x over previous
; DI void phase_scan(int wid0, const Params& p, unsigned char* lds, bool dry) {
;     ...
;             const unsigned vao = vs_base + (unsigned)(cur * 9216 + (8 * l4 + (l15 >> 2)) * 144 + 2 * (16 * cb0 + 4 * (l15 & 3)));
;             const unsigned vau = vs_base + (unsigned)(cur * 9216 + (8 * hi + (l15 >> 2)) * 144 + 2 * (16 * ((lane >> 4) & 1) + 4 * (l15 & 3)));
;             s16x4 ol[2][2], oh[2][2], ul0[4], uh0[4], ul1[4], uh1[4];
; #pragma unroll
;             for (int cc = 0; cc < 2; ++cc)
; #pragma unroll
;                 for (int s = 0; s < 2; ++s) { ol[cc][s] = tr_read0(vao + cc * 32 + s * 32 * 144); oh[cc][s] = tr_read0(vao + cc * 32 + s * 32 * 144 + 4 * 144); }
; #pragma unroll
;             for (int s = 0; s < 2; ++s) {
;                 ul0[s] = tr_read0(vau + s * 16 * 144); uh0[s] = tr_read0(vau + s * 16 * 144 + 4 * 144);
;                 ul1[s] = tr_read0(vau + s * 16 * 144 + 64); uh1[s] = tr_read0(vau + s * 16 * 144 + 4 * 144 + 64);
;             }
;             {
;                 __builtin_amdgcn_sched_barrier(0);
;                 f32x4 oacc[2];
; #pragma unroll
;                 for (int cc = 0; cc < 2; ++cc) {
;                     const int cb = cb0 + cc; oacc[cc] = (f32x4){0.f, 0.f, 0.f, 0.f};
; #pragma unroll
;                     for (int s = 0; s < 2; ++s) oacc[cc] = MFMA16(PK8(ol[cc][s], oh[cc][s]), at[s], oacc[cc]);
;                     const bf16_t* sp = sbt + cur * 16896 + (16 * cb + l15) * 264 + 8 * l4;
; #pragma unroll
;                     for (int s = 0; s < 8; ++s) { const bf16x8 bfr = *(const bf16x8*)(sp + 32 * s); oacc[cc] = MFMA16(bfr, aq[s], oacc[cc]); }
;                 }
; #pragma unroll
;                 for (int s = 2; s < 4; ++s) {
;                     ul0[s] = tr_read0(vau + s * 16 * 144); uh0[s] = tr_read0(vau + s * 16 * 144 + 4 * 144);
;                     ul1[s] = tr_read0(vau + s * 16 * 144 + 64); uh1[s] = tr_read0(vau + s * 16 * 144 + 4 * 144 + 64);
;                 }
; #pragma unroll
;                 for (int cc = 0; cc < 2; ++cc) {
;                     const int col = colv + 16 * (cb0 + cc) + 4 * l4;
;                     u32x2 w; w.x = cvt_pk_bf16(oacc[cc][0], oacc[cc][1]); w.y = cvt_pk_bf16(oacc[cc][2], oacc[cc][3]);
;                     if (dry) {} else if (c > 0) *(u32x2*)(vb + (size_t)(row0 + i) * 2048 + col) = w;
.LBB0_239:
	v_add_u32_e32 v62, s9, v181
	v_add_u32_e32 v179, s9, v180
	ds_read_b64_tr_b16 v[198:199], v62 offset:576
	ds_read_b64_tr_b16 v[196:197], v62
	ds_read_b64_tr_b16 v[202:203], v62 offset:608
	ds_read_b64_tr_b16 v[200:201], v62 offset:32
	ds_read_b64_tr_b16 v[204:205], v62 offset:4608
	ds_read_b64_tr_b16 v[206:207], v62 offset:5184
	ds_read_b64_tr_b16 v[210:211], v62 offset:5216
	ds_read_b64_tr_b16 v[208:209], v62 offset:4640
	ds_read_b64_tr_b16 v[82:83], v179
	ds_read_b64_tr_b16 v[84:85], v179 offset:576
	ds_read_b64_tr_b16 v[80:81], v179 offset:640
	ds_read_b64_tr_b16 v[78:79], v179 offset:64
	ds_read_b64_tr_b16 v[74:75], v179 offset:2304
	ds_read_b64_tr_b16 v[76:77], v179 offset:2880
	ds_read_b64_tr_b16 v[64:65], v179 offset:2944
	ds_read_b64_tr_b16 v[62:63], v179 offset:2368
	s_waitcnt vmcnt(17) lgkmcnt(14)
	v_mfma_f32_16x16x32_bf16 v[196:199], v[196:199], v[118:121], 0
	s_mul_i32 s9, s7, 0x8400
	v_add_u32_e32 v212, s9, v182
	v_add_u32_e32 v213, v212, v145
	s_waitcnt lgkmcnt(12)
	v_mfma_f32_16x16x32_bf16 v[118:121], v[200:203], v[118:121], 0
	v_add_u32_e32 v200, v212, v189
	s_waitcnt vmcnt(0)
	v_pk_mul_f32 v[32:33], v[32:33], v[72:73]
	v_pk_mul_f32 v[28:29], v[28:29], v[60:61]
	s_waitcnt lgkmcnt(10)
	v_mfma_f32_16x16x32_bf16 v[196:199], v[204:207], v[122:125], v[196:199]
	ds_read_b128 v[214:217], v213
	v_pk_mul_f32 v[24:25], v[24:25], v[56:57]
	v_pk_mul_f32 v[20:21], v[20:21], v[68:69]
	s_waitcnt lgkmcnt(9)
	v_mfma_f32_16x16x32_bf16 v[118:121], v[208:211], v[122:125], v[118:121]
	ds_read_b128 v[218:221], v200
	v_pk_mul_f32 v[18:19], v[18:19], v[66:67]
	v_pk_mul_f32 v[30:31], v[30:31], v[70:71]
	ds_read_b128 v[222:225], v213 offset:64
	ds_read_b128 v[226:229], v200 offset:64
	s_waitcnt lgkmcnt(3)
	v_mfma_f32_16x16x32_bf16 v[196:199], v[214:217], v[114:117], v[196:199]
	v_pk_mul_f32 v[26:27], v[26:27], v[58:59]
	v_pk_mul_f32 v[22:23], v[22:23], v[54:55]
	ds_read_b128 v[236:239], v213 offset:128
	s_waitcnt lgkmcnt(3)
	v_mfma_f32_16x16x32_bf16 v[114:117], v[218:221], v[114:117], v[118:121]
	v_mul_f32_e64 v16, v16, v72
	v_mul_f32_e64 v17, v17, v73
	v_pk_mul_f32 v[12:13], v[12:13], v[60:61]
	v_pk_mul_f32 v[8:9], v[8:9], v[56:57]
	ds_read_b128 v[240:243], v200 offset:128
	s_waitcnt lgkmcnt(3)
	v_mfma_f32_16x16x32_bf16 v[196:199], v[222:225], v[98:101], v[196:199]
	v_pk_mul_f32 v[4:5], v[4:5], v[68:69]
	v_pk_mul_f32 v[2:3], v[2:3], v[66:67]
	ds_read_b128 v[248:251], v213 offset:192
	s_waitcnt lgkmcnt(3)
	v_mfma_f32_16x16x32_bf16 v[98:101], v[226:229], v[98:101], v[114:117]
	s_nop 2
	v_pk_mul_f32 v[14:15], v[14:15], v[70:71]
	v_pk_mul_f32 v[10:11], v[10:11], v[58:59]
	ds_read_b128 v[252:255], v200 offset:192
	s_waitcnt lgkmcnt(3)
	v_mfma_f32_16x16x32_bf16 v[196:199], v[236:239], v[110:113], v[196:199]
	v_pk_mul_f32 v[6:7], v[6:7], v[54:55]
	ds_read_b128 v[214:217], v213 offset:256
	s_waitcnt lgkmcnt(3)
	v_mfma_f32_16x16x32_bf16 v[98:101], v[240:243], v[110:113], v[98:101]
	ds_read_b128 v[218:221], v200 offset:256
	s_waitcnt lgkmcnt(3)
	v_mfma_f32_16x16x32_bf16 v[196:199], v[248:251], v[86:89], v[196:199]
	ds_read_b128 v[222:225], v213 offset:320
	s_waitcnt lgkmcnt(3)
	v_mfma_f32_16x16x32_bf16 v[86:89], v[252:255], v[86:89], v[98:101]
	s_nop 2
	ds_read_b128 v[226:229], v200 offset:320
	s_waitcnt lgkmcnt(3)
	v_mfma_f32_16x16x32_bf16 v[196:199], v[214:217], v[102:105], v[196:199]
	ds_read_b128 v[236:239], v213 offset:384
	s_waitcnt lgkmcnt(3)
	v_mfma_f32_16x16x32_bf16 v[86:89], v[218:221], v[102:105], v[86:89]
	ds_read_b128 v[240:243], v200 offset:384
	s_waitcnt lgkmcnt(3)
	v_mfma_f32_16x16x32_bf16 v[196:199], v[222:225], v[90:93], v[196:199]
	ds_read_b128 v[248:251], v213 offset:448
	s_waitcnt lgkmcnt(3)
	v_mfma_f32_16x16x32_bf16 v[86:89], v[226:229], v[90:93], v[86:89]
	ds_read_b128 v[252:255], v200 offset:448
	s_waitcnt lgkmcnt(3)
	v_mfma_f32_16x16x32_bf16 v[196:199], v[236:239], v[106:109], v[196:199]
	s_waitcnt lgkmcnt(2)
	v_mfma_f32_16x16x32_bf16 v[86:89], v[240:243], v[106:109], v[86:89]
	v_add_u32_e32 v106, s8, v194
	v_ashrrev_i32_e32 v107, 31, v106
	s_waitcnt lgkmcnt(1)
	v_mfma_f32_16x16x32_bf16 v[196:199], v[248:251], v[94:97], v[196:199]
	v_lshlrev_b64 v[106:107], 12, v[106:107]
	v_lshl_add_u64 v[106:107], s[28:29], 0, v[106:107]
	v_lshl_add_u64 v[110:111], v[106:107], 0, v[0:1]
	s_waitcnt lgkmcnt(0)
	v_mfma_f32_16x16x32_bf16 v[86:89], v[252:255], v[94:97], v[86:89]
	ds_read_b64_tr_b16 v[90:91], v179 offset:4608
	ds_read_b64_tr_b16 v[92:93], v179 offset:5184
	ds_read_b64_tr_b16 v[94:95], v179 offset:4672
	ds_read_b64_tr_b16 v[96:97], v179 offset:5248
	ds_read_b64_tr_b16 v[98:99], v179 offset:6912
	ds_read_b64_tr_b16 v[100:101], v179 offset:7488
	ds_read_b64_tr_b16 v[102:103], v179 offset:6976
	ds_read_b64_tr_b16 v[104:105], v179 offset:7552
	v_mov_b32_e32 v179, v1
	v_cvt_pk_bf16_f32 v108, v196, v197
	v_cvt_pk_bf16_f32 v109, v198, v199
	v_cvt_pk_bf16_f32 v86, v86, v87
	v_cvt_pk_bf16_f32 v87, v88, v89
	v_lshl_add_u64 v[88:89], v[106:107], 0, v[178:179]
	global_store_dwordx2 v[110:111], v[108:109], off
	global_store_dwordx2 v[88:89], v[86:87], off
	v_mfma_f32_32x32x16_bf16 v[18:33], v[50:53], v[82:85], v[18:33]
	s_xor_b32 s7, s7, 1
	s_mul_i32 s7, s7, 0x8400
	s_add_i32 s8, s8, 64
	s_add_i32 s6, s6, 4
	s_add_i32 s2, s2, 1
	s_cmpk_eq_i32 s8, 0x1000
	v_mfma_f32_32x32x16_bf16 v[2:17], v[50:53], v[78:81], v[2:17]
	v_mfma_f32_32x32x16_bf16 v[18:33], v[46:49], v[74:77], v[18:33]
	v_mfma_f32_32x32x16_bf16 v[2:17], v[46:49], v[62:65], v[2:17]
	v_add_u32_e32 v46, s7, v131
	v_add_u32_e32 v47, 0x4000, v46
	s_waitcnt lgkmcnt(6)
	v_mfma_f32_32x32x16_bf16 v[18:33], v[42:45], v[90:93], v[18:33]
	s_waitcnt lgkmcnt(4)
	v_mfma_f32_32x32x16_bf16 v[2:17], v[42:45], v[94:97], v[2:17]
	s_waitcnt lgkmcnt(2)
	v_mfma_f32_32x32x16_bf16 v[18:33], v[38:41], v[98:101], v[18:33]
	s_waitcnt lgkmcnt(0)
	v_mfma_f32_32x32x16_bf16 v[2:17], v[38:41], v[102:105], v[2:17]
	s_nop 9
	v_cvt_pk_bf16_f32 v42, v18, v19
	v_cvt_pk_bf16_f32 v43, v20, v21
	v_cvt_pk_bf16_f32 v40, v22, v23
	v_cvt_pk_bf16_f32 v41, v24, v25
	ds_write2_b64 v46, v[42:43], v[40:41] offset1:2
	v_cvt_pk_bf16_f32 v42, v30, v31
	v_cvt_pk_bf16_f32 v43, v32, v33
	v_cvt_pk_bf16_f32 v38, v2, v3
	v_cvt_pk_bf16_f32 v39, v4, v5
	v_cvt_pk_bf16_f32 v44, v6, v7
	v_cvt_pk_bf16_f32 v45, v8, v9
	ds_write2_b64 v47, v[38:39], v[44:45] offset0:64 offset1:66
	v_cvt_pk_bf16_f32 v38, v26, v27
	v_cvt_pk_bf16_f32 v39, v28, v29
	v_cvt_pk_bf16_f32 v40, v10, v11
	v_cvt_pk_bf16_f32 v41, v12, v13
	v_cvt_pk_bf16_f32 v44, v14, v15
	v_cvt_pk_bf16_f32 v45, v16, v17
	ds_write2_b64 v46, v[38:39], v[42:43] offset0:4 offset1:6
	ds_write2_b64 v47, v[40:41], v[44:45] offset0:68 offset1:70
	s_cbranch_scc1 .LBB0_228
